# DeltaNet chain: static priority raise (s_setprio 2) for the output-path waves, the longer of the two wave roles in a step; reset at the end of the section
# speedup vs baseline: 1.0048x; 1.0048x over previous
.LBB0_1013:
	s_mov_b64 s[38:39], -1
	s_and_b64 vcc, exec, s[12:13]
	s_cbranch_vccz .LBB0_1017
	s_setprio 2
	s_waitcnt vmcnt(14)
	v_mov_b64_e32 v[110:111], v[210:211]
	v_mov_b64_e32 v[112:113], v[212:213]
	v_mov_b64_e32 v[106:107], v[214:215]
	v_mov_b64_e32 v[108:109], v[216:217]
	v_readlane_b32 s6, v248, 44
	v_readlane_b32 s7, v248, 45
	s_nop 1
	v_lshl_add_u64 v[210:211], v[128:129], 0, s[6:7]
	s_mov_b64 s[6:7], 0x9951000
	v_lshl_add_u64 v[214:215], v[210:211], 0, s[6:7]
	global_load_dwordx4 v[210:213], v[214:215], off
	s_nop 0
	global_load_dwordx4 v[214:217], v[214:215], off offset:16
	s_cmp_eq_u32 s0, 0
	s_cbranch_scc1 .Lc_c0loads
	ds_read_b128 v[118:121], v123
	ds_read_b128 v[114:117], v123 offset:16
	ds_read_b128 v[102:105], v123 offset:32
	ds_read_b128 v[98:101], v123 offset:48
	v_lshlrev_b32_e32 v66, 16, v110
	v_and_b32_e32 v67, 0xffff0000, v110
	v_lshlrev_b32_e32 v68, 16, v111
	v_and_b32_e32 v69, 0xffff0000, v111
	v_lshlrev_b32_e32 v70, 16, v112
	v_and_b32_e32 v71, 0xffff0000, v112
	v_lshlrev_b32_e32 v72, 16, v113
	v_and_b32_e32 v73, 0xffff0000, v113
	v_lshlrev_b32_e32 v74, 16, v106
	v_and_b32_e32 v75, 0xffff0000, v106
	v_lshlrev_b32_e32 v76, 16, v107
	v_and_b32_e32 v77, 0xffff0000, v107
	v_lshlrev_b32_e32 v78, 16, v108
	v_and_b32_e32 v79, 0xffff0000, v108
	v_lshlrev_b32_e32 v80, 16, v109
	v_and_b32_e32 v81, 0xffff0000, v109
	v_mul_f32_e32 v82, 0xbfb8aa3b, v66
	v_mul_f32_e32 v83, 0xbfb8aa3b, v67
	v_mul_f32_e32 v84, 0xbfb8aa3b, v68
	v_mul_f32_e32 v85, 0xbfb8aa3b, v69
	v_mul_f32_e32 v86, 0xbfb8aa3b, v70
	v_mul_f32_e32 v87, 0xbfb8aa3b, v71
	v_mul_f32_e32 v88, 0xbfb8aa3b, v72
	v_mul_f32_e32 v89, 0xbfb8aa3b, v73
	v_mul_f32_e32 v2, 0xbfb8aa3b, v74
	v_mul_f32_e32 v3, 0xbfb8aa3b, v75
	v_mul_f32_e32 v4, 0xbfb8aa3b, v76
	v_mul_f32_e32 v5, 0xbfb8aa3b, v77
	v_mul_f32_e32 v22, 0xbfb8aa3b, v78
	v_mul_f32_e32 v23, 0xbfb8aa3b, v79
	v_mul_f32_e32 v24, 0xbfb8aa3b, v80
	v_mul_f32_e32 v25, 0xbfb8aa3b, v81
	s_cmp_gt_u32 s0, 29
	s_cbranch_scc1 .Lc_dl0A
	s_mov_b64 s[6:7], 0x1ad10000
	v_lshl_add_u64 v[26:27], v[136:137], 0, s[6:7]
	global_load_dwordx4 v[26:29], v[26:27], off

.LBB0_1016:
	s_setprio 0
	s_mov_b64 s[38:39], 0

.LBB0_1022:
	s_mov_b64 s[20:21], -1
	s_and_b64 vcc, exec, s[12:13]
	s_cbranch_vccz .LBB0_1024
	s_setprio 2
	s_waitcnt vmcnt(14)
	v_mov_b64_e32 v[94:95], v[218:219]
	v_mov_b64_e32 v[96:97], v[220:221]
	v_mov_b64_e32 v[90:91], v[222:223]
	v_mov_b64_e32 v[92:93], v[224:225]
	s_cmp_gt_u32 s0, 28
	s_cbranch_scc1 .Lc_noze
	v_readlane_b32 s6, v248, 44
	v_readlane_b32 s7, v248, 45
	s_nop 1
	v_lshl_add_u64 v[218:219], v[128:129], 0, s[6:7]
	s_mov_b64 s[6:7], 0x99a1000
	v_lshl_add_u64 v[222:223], v[218:219], 0, s[6:7]
	global_load_dwordx4 v[218:221], v[222:223], off
	s_nop 0
	global_load_dwordx4 v[222:225], v[222:223], off offset:16

.Lc_dl4B:
	v_pk_mul_f32 v[66:67], v[82:83], v[66:67]
	v_pk_mul_f32 v[68:69], v[84:85], v[68:69]
	v_pk_mul_f32 v[70:71], v[86:87], v[70:71]
	v_pk_mul_f32 v[72:73], v[88:89], v[72:73]
	v_pk_mul_f32 v[74:75], v[2:3], v[74:75]
	v_pk_mul_f32 v[76:77], v[4:5], v[76:77]
	v_pk_mul_f32 v[78:79], v[22:23], v[78:79]
	v_pk_mul_f32 v[80:81], v[24:25], v[80:81]
	v_pk_mul_f32 v[180:181], v[18:19], v[140:141] op_sel_hi:[1,0]
	v_pk_mul_f32 v[182:183], v[20:21], v[140:141] op_sel_hi:[1,0]
	v_pk_mul_f32 v[184:185], v[14:15], v[140:141] op_sel_hi:[1,0]
	v_pk_mul_f32 v[186:187], v[16:17], v[140:141] op_sel_hi:[1,0]
	v_pk_mul_f32 v[188:189], v[10:11], v[140:141] op_sel_hi:[1,0]
	v_pk_mul_f32 v[190:191], v[12:13], v[140:141] op_sel_hi:[1,0]
	v_pk_mul_f32 v[192:193], v[6:7], v[140:141] op_sel_hi:[1,0]
	v_pk_mul_f32 v[194:195], v[8:9], v[140:141] op_sel_hi:[1,0]
	v_pk_mul_f32 v[180:181], v[118:119], v[180:181]
	v_pk_mul_f32 v[182:183], v[120:121], v[182:183]
	v_pk_mul_f32 v[184:185], v[114:115], v[184:185]
	v_pk_mul_f32 v[186:187], v[116:117], v[186:187]
	v_pk_mul_f32 v[188:189], v[110:111], v[188:189]
	v_pk_mul_f32 v[190:191], v[112:113], v[190:191]
	v_pk_mul_f32 v[192:193], v[106:107], v[192:193]
	v_pk_mul_f32 v[194:195], v[108:109], v[194:195]
	v_pk_mul_f32 v[66:67], v[66:67], v[180:181]
	v_pk_mul_f32 v[68:69], v[68:69], v[182:183]
	v_pk_mul_f32 v[70:71], v[70:71], v[184:185]
	v_pk_mul_f32 v[72:73], v[72:73], v[186:187]
	v_pk_mul_f32 v[74:75], v[74:75], v[188:189]
	v_pk_mul_f32 v[76:77], v[76:77], v[190:191]
	v_pk_mul_f32 v[78:79], v[78:79], v[192:193]
	v_pk_mul_f32 v[80:81], v[80:81], v[194:195]
	v_cvt_pk_bf16_f32 v94, v66, v67
	v_cvt_pk_bf16_f32 v95, v68, v69
	v_cvt_pk_bf16_f32 v96, v70, v71
	v_cvt_pk_bf16_f32 v97, v72, v73
	v_cvt_pk_bf16_f32 v90, v74, v75
	v_cvt_pk_bf16_f32 v91, v76, v77
	v_cvt_pk_bf16_f32 v92, v78, v79
	v_cvt_pk_bf16_f32 v93, v80, v81
	v_readlane_b32 s6, v248, 44
	v_readlane_b32 s7, v248, 45
	s_mov_b64 s[20:21], 0
	s_nop 0
	v_lshl_add_u64 v[106:107], v[132:133], 0, s[6:7]
	global_store_dwordx4 v[106:107], v[94:97], off offset:1536
	global_store_dwordx4 v[106:107], v[90:93], off offset:1552
	s_setprio 0
